# v28 plus packed fma of the attention accumulator init split into scalar fma pairs
# speedup vs baseline: 1.0010x; 1.0010x over previous
; #define LAS __attribute__((address_space(3)))
; __device__ __forceinline__ void attn_unit(LAS unsigned char* lds, const bf16* __restrict__ proj, bf16* __restrict__ mix, int b, int h, int qb, float lam, float sl2,
;                                           const float* __restrict__ sg, float oscale, const int tid_in) {
;     ...
;             float base = sl2 * (float)(kt * 64 + 4 * hi - qpos) - mref; asm volatile("" : "+v"(base));
; #pragma unroll
;             for (int r = 0; r < 16; ++r) { p0[r] = __builtin_fmaf(sl2, (float)((r & 3) + 8 * (r >> 2)), base); p1[r] = __builtin_fmaf(sl2, (float)((r & 3) + 8 * (r >> 2) + 32), base); }
; #pragma unroll
;             for (int d0 = 0; d0 < 4; ++d0) { const bf16x8 k0 = *(LAS const bf16x8*)(kc + d0 * 32), k1 = *(LAS const bf16x8*)(kc + 32 * KSTR + d0 * 32), qv = *(LAS const bf16x8*)(qs + d0 * 32);
;                 p0 = __builtin_amdgcn_mfma_f32_32x32x16_bf16(k0, qv, p0, 0, 0, 0); p1 = __builtin_amdgcn_mfma_f32_32x32x16_bf16(k1, qv, p1, 0, 0, 0); }
.LBB0_189:
	s_bitcmp1_b32 s0, 0
	v_add_u32_e32 v64, s12, v153
	v_cvt_f32_i32_e32 v64, v64
	s_cselect_b32 s0, 0x9800, 0
	s_add_i32 s16, s0, 0
	s_mul_i32 s0, s10, 0x2400
	s_add_i32 s0, s16, s0
	v_add3_u32 v204, s0, v141, v124
	s_mov_b32 s0, 0x41800000
	v_fma_f32 v84, v154, v64, -v202
	s_mov_b32 s1, 0x41880000
	v_mov_b32_e32 v155, v154
	v_fma_f32 v94, v156, s0, v84
	v_fma_f32 v95, v157, s1, v84
	s_mov_b32 s0, 0x41900000
	s_mov_b32 s1, 0x41980000
	v_fma_f32 v96, v156, s0, v84
	v_fma_f32 v97, v157, s1, v84
	s_mov_b32 s0, 0x41c00000
	s_mov_b32 s1, 0x41c80000
	v_fma_f32 v98, v156, s0, v84
	v_fma_f32 v99, v157, s1, v84
	s_mov_b32 s0, 0x41d00000
	s_mov_b32 s1, 0x41d80000
	v_fma_f32 v100, v156, s0, v84
	v_fma_f32 v101, v157, s1, v84
	s_mov_b32 s0, 0x42680000
	s_mov_b32 s1, 0x426c0000
	v_fma_f32 v78, v154, s0, v84
	v_fma_f32 v79, v155, s1, v84
	s_mov_b32 s0, 0x42600000
	s_mov_b32 s1, 0x42640000
	v_fma_f32 v76, v154, s0, v84
	v_fma_f32 v77, v155, s1, v84
	s_mov_b32 s0, 0x42480000
	ds_read_b128 v[64:67], v204
	ds_read_b128 v[226:229], v149
	s_mov_b32 s1, 0x424c0000
	v_fma_f32 v74, v154, s0, v84
	v_fma_f32 v75, v155, s1, v84
	s_mov_b32 s0, 0x42400000
	s_mov_b32 s1, 0x42440000
	ds_read_b128 v[230:233], v204 offset:4608
	v_fma_f32 v72, v154, s0, v84
	v_fma_f32 v73, v155, s1, v84
	s_mov_b32 s0, 0x42280000
	s_mov_b32 s36, 2.0
	s_mov_b32 s1, 0x422c0000
	s_mov_b32 s37, 0x40400000
	v_fma_f32 v70, v154, s0, v84
	v_fma_f32 v71, v155, s1, v84
	s_mov_b32 s0, 0x42200000
	v_fma_f32 v88, v156, s36, v84
	v_fma_f32 v89, v157, s37, v84
	s_mov_b32 s36, 0x41200000
	s_mov_b32 s1, 0x42240000
	s_mov_b32 s37, 0x41300000
	v_fma_f32 v68, v154, s0, v84
	v_fma_f32 v69, v155, s1, v84
	s_mov_b32 s0, 0x42080000
	v_fma_f32 v86, 0, v154, v84
	v_add_f32_e32 v87, v154, v84
	v_fma_f32 v90, v156, s82, v84
	v_fma_f32 v91, v157, s83, v84
	v_fma_f32 v92, v156, s36, v84
	v_fma_f32 v93, v157, s37, v84
	s_mov_b32 s1, 0x420c0000
	ds_read_b128 v[234:237], v204 offset:32
	ds_read_b128 v[238:241], v149 offset:32
	ds_read_b128 v[242:245], v204 offset:4640
	s_waitcnt lgkmcnt(4)
	v_mfma_f32_32x32x16_bf16 v[86:101], v[64:67], v[226:229], v[86:101]
	v_fma_f32 v66, v154, s0, v84
	v_fma_f32 v67, v155, s1, v84
	s_mov_b32 s0, 0x42000000
	s_mov_b32 s1, 0x42040000
	v_fma_f32 v64, v158, s0, v84
	v_fma_f32 v65, v159, s1, v84
	s_add_i32 s0, s12, 63
	s_cmp_le_u32 s0, s11
	s_waitcnt lgkmcnt(3)
	v_mfma_f32_32x32x16_bf16 v[64:79], v[230:233], v[226:229], v[64:79]
	ds_read_b128 v[246:249], v204 offset:64
	ds_read_b128 v[226:229], v149 offset:64
	ds_read_b128 v[230:233], v204 offset:4672
	s_waitcnt lgkmcnt(4)
	v_mfma_f32_32x32x16_bf16 v[86:101], v[234:237], v[238:241], v[86:101]
	s_waitcnt lgkmcnt(3)
	v_mfma_f32_32x32x16_bf16 v[64:79], v[242:245], v[238:241], v[64:79]
	ds_read_b128 v[234:237], v204 offset:96
	ds_read_b128 v[238:241], v149 offset:96
	ds_read_b128 v[242:245], v204 offset:4704
	s_waitcnt lgkmcnt(4)
	v_mfma_f32_32x32x16_bf16 v[86:101], v[246:249], v[226:229], v[86:101]
	s_waitcnt lgkmcnt(3)
	v_mfma_f32_32x32x16_bf16 v[64:79], v[230:233], v[226:229], v[64:79]
	s_waitcnt lgkmcnt(1)
	v_mfma_f32_32x32x16_bf16 v[86:101], v[234:237], v[238:241], v[86:101]
	s_waitcnt lgkmcnt(0)
	v_mfma_f32_32x32x16_bf16 v[64:79], v[242:245], v[238:241], v[64:79]
	s_cbranch_scc1 .LBB0_191
	v_cmp_gt_i32_e64 s[94:95], 26, v151
	v_cmp_gt_i32_e64 s[96:97], 27, v151
	v_cmp_gt_i32_e64 s[92:93], 25, v151
	s_and_b64 s[94:95], s[96:97], s[94:95]
	v_cmp_gt_i32_e64 s[90:91], 24, v151
	s_and_b64 s[92:93], s[94:95], s[92:93]
	v_cmp_gt_i32_e64 s[88:89], 19, v151
	s_and_b64 s[90:91], s[92:93], s[90:91]
	v_cmp_gt_i32_e64 s[86:87], 18, v151
	s_and_b64 s[88:89], s[90:91], s[88:89]
	v_cmp_gt_i32_e64 s[84:85], 17, v151
	s_and_b64 s[86:87], s[88:89], s[86:87]
	v_cmp_gt_i32_e64 s[80:81], 16, v151
	s_and_b64 s[84:85], s[86:87], s[84:85]
	v_cmp_gt_i32_e64 s[78:79], 11, v151
	s_and_b64 s[80:81], s[84:85], s[80:81]
	v_cmp_gt_i32_e64 s[76:77], 10, v151
	s_and_b64 s[78:79], s[80:81], s[78:79]
	v_cmp_gt_i32_e64 s[74:75], 9, v151
	s_and_b64 s[76:77], s[78:79], s[76:77]
	v_cmp_gt_i32_e64 s[72:73], 8, v151
	s_and_b64 s[74:75], s[76:77], s[74:75]
	v_cmp_gt_i32_e64 s[70:71], 3, v151
	s_and_b64 s[72:73], s[74:75], s[72:73]
	v_cmp_gt_i32_e64 s[68:69], 2, v151
	s_and_b64 s[70:71], s[72:73], s[70:71]
	v_cmp_gt_i32_e64 s[66:67], 1, v151
	s_and_b64 s[68:69], s[70:71], s[68:69]
	v_cmp_gt_i32_e64 s[64:65], 0, v151
	s_and_b64 s[66:67], s[68:69], s[66:67]
	s_and_b64 s[64:65], s[66:67], s[64:65]
	v_cmp_gt_i32_e64 s[62:63], 58, v151
	v_cndmask_b32_e64 v86, v86, v221, s[64:65]
	v_cmp_gt_i32_e64 s[64:65], 59, v151
	v_cmp_gt_i32_e64 s[60:61], 57, v151
	s_and_b64 s[62:63], s[64:65], s[62:63]
	v_cmp_gt_i32_e64 s[58:59], 56, v151
	s_and_b64 s[60:61], s[62:63], s[60:61]
	v_cmp_gt_i32_e64 s[56:57], 51, v151
	s_and_b64 s[58:59], s[60:61], s[58:59]
	v_cmp_gt_i32_e64 s[54:55], 50, v151
	s_and_b64 s[56:57], s[58:59], s[56:57]
	v_cmp_gt_i32_e64 s[50:51], 49, v151
	s_and_b64 s[54:55], s[56:57], s[54:55]
	v_cmp_gt_i32_e64 s[48:49], 48, v151
	s_and_b64 s[50:51], s[54:55], s[50:51]
	v_cmp_gt_i32_e64 s[46:47], 43, v151
	s_and_b64 s[48:49], s[50:51], s[48:49]
	v_cmp_gt_i32_e64 s[44:45], 42, v151
	s_and_b64 s[46:47], s[48:49], s[46:47]
	v_cmp_gt_i32_e64 s[42:43], 41, v151
	s_and_b64 s[44:45], s[46:47], s[44:45]
	v_cmp_gt_i32_e64 s[40:41], 40, v151
	s_and_b64 s[42:43], s[44:45], s[42:43]
	v_cmp_gt_i32_e64 s[38:39], 35, v151
	s_and_b64 s[40:41], s[42:43], s[40:41]
	v_cmp_gt_i32_e64 s[36:37], 34, v151
	s_and_b64 s[38:39], s[40:41], s[38:39]
	v_cmp_gt_i32_e64 s[0:1], 33, v151
	s_and_b64 s[36:37], s[38:39], s[36:37]
	v_cmp_gt_i32_e32 vcc, 32, v151
	s_and_b64 s[0:1], s[36:37], s[0:1]
	v_cndmask_b32_e64 v88, v88, v221, s[68:69]
	v_readlane_b32 s68, v255, 2
	s_and_b64 vcc, s[0:1], vcc
	v_cndmask_b32_e64 v101, v101, v221, s[96:97]
	v_cndmask_b32_e64 v100, v100, v221, s[94:95]
	v_cndmask_b32_e64 v99, v99, v221, s[92:93]
	v_cndmask_b32_e64 v98, v98, v221, s[90:91]
	v_cndmask_b32_e64 v97, v97, v221, s[88:89]
	v_cndmask_b32_e64 v96, v96, v221, s[86:87]
	v_cndmask_b32_e64 v95, v95, v221, s[84:85]
	v_cndmask_b32_e64 v94, v94, v221, s[80:81]
	v_cndmask_b32_e64 v93, v93, v221, s[78:79]
	v_cndmask_b32_e64 v92, v92, v221, s[76:77]
	v_cndmask_b32_e64 v91, v91, v221, s[74:75]
	v_cndmask_b32_e64 v90, v90, v221, s[72:73]
	s_mov_b32 s72, s18
	v_cndmask_b32_e64 v89, v89, v221, s[70:71]
	v_readlane_b32 s71, v255, 13
	v_readlane_b32 s19, v255, 12
	v_readlane_b32 s70, v255, 11
	v_readlane_b32 s69, v255, 3
	v_cndmask_b32_e64 v87, v87, v221, s[66:67]
	v_cndmask_b32_e64 v79, v79, v221, s[64:65]
	v_cndmask_b32_e64 v78, v78, v221, s[62:63]
	s_mov_b32 s62, s26
	v_cndmask_b32_e64 v77, v77, v221, s[60:61]
	v_cndmask_b32_e64 v76, v76, v221, s[58:59]
	v_cndmask_b32_e64 v75, v75, v221, s[56:57]
	v_cndmask_b32_e64 v74, v74, v221, s[54:55]
	v_cndmask_b32_e64 v73, v73, v221, s[50:51]
	v_cndmask_b32_e64 v72, v72, v221, s[48:49]
	v_cndmask_b32_e64 v71, v71, v221, s[46:47]
	v_cndmask_b32_e64 v70, v70, v221, s[44:45]
	v_cndmask_b32_e64 v69, v69, v221, s[42:43]
	v_cndmask_b32_e64 v68, v68, v221, s[40:41]
	v_cndmask_b32_e64 v67, v67, v221, s[38:39]
	v_cndmask_b32_e64 v66, v66, v221, s[36:37]
	v_cndmask_b32_e64 v65, v65, v221, s[0:1]
	v_cndmask_b32_e32 v64, v64, v221, vcc

.LBB0_206:
	s_bitcmp1_b32 s0, 0
	v_add_u32_e32 v64, s6, v153
	v_cvt_f32_i32_e32 v64, v64
	s_cselect_b32 s0, 0x9800, 0
	s_add_i32 s13, s0, 0
	s_mul_i32 s0, s8, 0x2400
	s_add_i32 s0, s13, s0
	v_add3_u32 v216, s0, v141, v124
	s_mov_b32 s0, 0x41800000
	v_fma_f32 v84, v154, v64, -v164
	s_mov_b32 s1, 0x41880000
	v_mov_b32_e32 v155, v154
	v_fma_f32 v94, v156, s0, v84
	v_fma_f32 v95, v157, s1, v84
	s_mov_b32 s0, 0x41900000
	s_mov_b32 s1, 0x41980000
	v_fma_f32 v96, v156, s0, v84
	v_fma_f32 v97, v157, s1, v84
	s_mov_b32 s0, 0x41c00000
	s_mov_b32 s1, 0x41c80000
	v_fma_f32 v98, v156, s0, v84
	v_fma_f32 v99, v157, s1, v84
	s_mov_b32 s0, 0x41d00000
	s_mov_b32 s1, 0x41d80000
	v_fma_f32 v100, v156, s0, v84
	v_fma_f32 v101, v157, s1, v84
	s_mov_b32 s0, 0x42680000
	s_mov_b32 s1, 0x426c0000
	v_fma_f32 v78, v154, s0, v84
	v_fma_f32 v79, v155, s1, v84
	s_mov_b32 s0, 0x42600000
	s_mov_b32 s1, 0x42640000
	v_fma_f32 v76, v154, s0, v84
	v_fma_f32 v77, v155, s1, v84
	s_mov_b32 s0, 0x42480000
	ds_read_b128 v[64:67], v216
	ds_read_b128 v[166:169], v149
	s_mov_b32 s1, 0x424c0000
	v_fma_f32 v74, v154, s0, v84
	v_fma_f32 v75, v155, s1, v84
	s_mov_b32 s0, 0x42400000
	s_mov_b32 s1, 0x42440000
	ds_read_b128 v[202:205], v216 offset:4608
	v_fma_f32 v72, v154, s0, v84
	v_fma_f32 v73, v155, s1, v84
	s_mov_b32 s0, 0x42280000
	s_mov_b32 s14, 2.0
	s_mov_b32 s1, 0x422c0000
	s_mov_b32 s15, 0x40400000
	v_fma_f32 v70, v154, s0, v84
	v_fma_f32 v71, v155, s1, v84
	s_mov_b32 s0, 0x42200000
	v_fma_f32 v88, v156, s14, v84
	v_fma_f32 v89, v157, s15, v84
	s_mov_b32 s14, 0x41200000
	s_mov_b32 s1, 0x42240000
	s_mov_b32 s15, 0x41300000
	v_fma_f32 v68, v154, s0, v84
	v_fma_f32 v69, v155, s1, v84
	s_mov_b32 s0, 0x42080000
	v_fma_f32 v86, 0, v154, v84
	v_add_f32_e32 v87, v154, v84
	v_fma_f32 v90, v156, s82, v84
	v_fma_f32 v91, v157, s83, v84
	v_fma_f32 v92, v156, s14, v84
	v_fma_f32 v93, v157, s15, v84
	s_mov_b32 s1, 0x420c0000
	ds_read_b128 v[234:237], v216 offset:32
	ds_read_b128 v[238:241], v149 offset:32
	ds_read_b128 v[242:245], v216 offset:4640
	s_waitcnt lgkmcnt(4)
	v_mfma_f32_32x32x16_bf16 v[86:101], v[64:67], v[166:169], v[86:101]
	v_fma_f32 v66, v154, s0, v84
	v_fma_f32 v67, v155, s1, v84
	s_mov_b32 s0, 0x42000000
	s_mov_b32 s1, 0x42040000
	v_fma_f32 v64, v158, s0, v84
	v_fma_f32 v65, v159, s1, v84
	s_add_i32 s0, s6, 63
	s_cmp_le_u32 s0, s9
	s_waitcnt lgkmcnt(3)
	v_mfma_f32_32x32x16_bf16 v[64:79], v[202:205], v[166:169], v[64:79]
	ds_read_b128 v[246:249], v216 offset:64
	ds_read_b128 v[166:169], v149 offset:64
	ds_read_b128 v[202:205], v216 offset:4672
	s_waitcnt lgkmcnt(4)
	v_mfma_f32_32x32x16_bf16 v[86:101], v[234:237], v[238:241], v[86:101]
	s_waitcnt lgkmcnt(3)
	v_mfma_f32_32x32x16_bf16 v[64:79], v[242:245], v[238:241], v[64:79]
	ds_read_b128 v[234:237], v216 offset:96
	ds_read_b128 v[238:241], v149 offset:96
	ds_read_b128 v[242:245], v216 offset:4704
	s_waitcnt lgkmcnt(4)
	v_mfma_f32_32x32x16_bf16 v[86:101], v[246:249], v[166:169], v[86:101]
	s_waitcnt lgkmcnt(3)
	v_mfma_f32_32x32x16_bf16 v[64:79], v[202:205], v[166:169], v[64:79]
	s_waitcnt lgkmcnt(1)
	v_mfma_f32_32x32x16_bf16 v[86:101], v[234:237], v[238:241], v[86:101]
	s_waitcnt lgkmcnt(0)
	v_mfma_f32_32x32x16_bf16 v[64:79], v[242:245], v[238:241], v[64:79]
	s_cbranch_scc1 .LBB0_208
	v_cmp_gt_i32_e64 s[94:95], 26, v151
	v_cmp_gt_i32_e64 s[96:97], 27, v151
	v_cmp_gt_i32_e64 s[92:93], 25, v151
	s_and_b64 s[94:95], s[96:97], s[94:95]
	v_cmp_gt_i32_e64 s[90:91], 24, v151
	s_and_b64 s[92:93], s[94:95], s[92:93]
	v_cmp_gt_i32_e64 s[88:89], 19, v151
	s_and_b64 s[90:91], s[92:93], s[90:91]
	v_cmp_gt_i32_e64 s[86:87], 18, v151
	s_and_b64 s[88:89], s[90:91], s[88:89]
	v_cmp_gt_i32_e64 s[84:85], 17, v151
	s_and_b64 s[86:87], s[88:89], s[86:87]
	v_cmp_gt_i32_e64 s[80:81], 16, v151
	s_and_b64 s[84:85], s[86:87], s[84:85]
	v_cmp_gt_i32_e64 s[78:79], 11, v151
	s_and_b64 s[80:81], s[84:85], s[80:81]
	v_cmp_gt_i32_e64 s[76:77], 10, v151
	s_and_b64 s[78:79], s[80:81], s[78:79]
	v_cmp_gt_i32_e64 s[74:75], 9, v151
	s_and_b64 s[76:77], s[78:79], s[76:77]
	v_cmp_gt_i32_e64 s[72:73], 8, v151
	s_and_b64 s[74:75], s[76:77], s[74:75]
	v_cmp_gt_i32_e64 s[70:71], 3, v151
	s_and_b64 s[72:73], s[74:75], s[72:73]
	v_cmp_gt_i32_e64 s[68:69], 2, v151
	s_and_b64 s[70:71], s[72:73], s[70:71]
	v_cmp_gt_i32_e64 s[66:67], 1, v151
	s_and_b64 s[68:69], s[70:71], s[68:69]
	v_cmp_gt_i32_e64 s[64:65], 0, v151
	s_and_b64 s[66:67], s[68:69], s[66:67]
	s_and_b64 s[64:65], s[66:67], s[64:65]
	v_cmp_gt_i32_e64 s[62:63], 58, v151
	v_cndmask_b32_e64 v86, v86, v221, s[64:65]
	v_cmp_gt_i32_e64 s[64:65], 59, v151
	v_cmp_gt_i32_e64 s[60:61], 57, v151
	s_and_b64 s[62:63], s[64:65], s[62:63]
	v_cmp_gt_i32_e64 s[58:59], 56, v151
	s_and_b64 s[60:61], s[62:63], s[60:61]
	v_cmp_gt_i32_e64 s[56:57], 51, v151
	s_and_b64 s[58:59], s[60:61], s[58:59]
	v_cmp_gt_i32_e64 s[54:55], 50, v151
	s_and_b64 s[56:57], s[58:59], s[56:57]
	v_cmp_gt_i32_e64 s[50:51], 49, v151
	s_and_b64 s[54:55], s[56:57], s[54:55]
	v_cmp_gt_i32_e64 s[48:49], 48, v151
	s_and_b64 s[50:51], s[54:55], s[50:51]
	v_cmp_gt_i32_e64 s[46:47], 43, v151
	s_and_b64 s[48:49], s[50:51], s[48:49]
	v_cmp_gt_i32_e64 s[44:45], 42, v151
	s_and_b64 s[46:47], s[48:49], s[46:47]
	v_cmp_gt_i32_e64 s[42:43], 41, v151
	s_and_b64 s[44:45], s[46:47], s[44:45]
	v_cmp_gt_i32_e64 s[40:41], 40, v151
	s_and_b64 s[42:43], s[44:45], s[42:43]
	v_cmp_gt_i32_e64 s[38:39], 35, v151
	s_and_b64 s[40:41], s[42:43], s[40:41]
	v_cmp_gt_i32_e64 s[36:37], 34, v151
	s_and_b64 s[38:39], s[40:41], s[38:39]
	v_cmp_gt_i32_e64 s[0:1], 33, v151
	s_and_b64 s[36:37], s[38:39], s[36:37]
	v_cmp_gt_i32_e32 vcc, 32, v151
	s_and_b64 s[0:1], s[36:37], s[0:1]
	v_cndmask_b32_e64 v88, v88, v221, s[68:69]
	v_readlane_b32 s68, v255, 2
	s_and_b64 vcc, s[0:1], vcc
	v_cndmask_b32_e64 v101, v101, v221, s[96:97]
	v_cndmask_b32_e64 v100, v100, v221, s[94:95]
	v_cndmask_b32_e64 v99, v99, v221, s[92:93]
	v_cndmask_b32_e64 v98, v98, v221, s[90:91]
	v_cndmask_b32_e64 v97, v97, v221, s[88:89]
	v_cndmask_b32_e64 v96, v96, v221, s[86:87]
	v_cndmask_b32_e64 v95, v95, v221, s[84:85]
	v_cndmask_b32_e64 v94, v94, v221, s[80:81]
	v_cndmask_b32_e64 v93, v93, v221, s[78:79]
	v_cndmask_b32_e64 v92, v92, v221, s[76:77]
	v_cndmask_b32_e64 v91, v91, v221, s[74:75]
	v_cndmask_b32_e64 v90, v90, v221, s[72:73]
	s_mov_b32 s72, s18
	v_cndmask_b32_e64 v89, v89, v221, s[70:71]
	v_readlane_b32 s71, v255, 13
	v_readlane_b32 s19, v255, 12
	v_readlane_b32 s70, v255, 11
	v_readlane_b32 s69, v255, 3
	v_cndmask_b32_e64 v87, v87, v221, s[66:67]
	v_cndmask_b32_e64 v79, v79, v221, s[64:65]
	v_cndmask_b32_e64 v78, v78, v221, s[62:63]
	s_mov_b32 s62, s26
	v_cndmask_b32_e64 v77, v77, v221, s[60:61]
	v_cndmask_b32_e64 v76, v76, v221, s[58:59]
	v_cndmask_b32_e64 v75, v75, v221, s[56:57]
	v_cndmask_b32_e64 v74, v74, v221, s[54:55]
	v_cndmask_b32_e64 v73, v73, v221, s[50:51]
	v_cndmask_b32_e64 v72, v72, v221, s[48:49]
	v_cndmask_b32_e64 v71, v71, v221, s[46:47]
	v_cndmask_b32_e64 v70, v70, v221, s[44:45]
	v_cndmask_b32_e64 v69, v69, v221, s[42:43]
	v_cndmask_b32_e64 v68, v68, v221, s[40:41]
	v_cndmask_b32_e64 v67, v67, v221, s[38:39]
	v_cndmask_b32_e64 v66, v66, v221, s[36:37]
	v_cndmask_b32_e64 v65, v65, v221, s[0:1]
	v_cndmask_b32_e32 v64, v64, v221, vcc
